# recurrence / S5 prompt items that share q,k,gate rows or 128 B lines are assigned to workgroups of one XCD (item index bit permutation when half the grid is 128)
# speedup vs baseline: 1.0113x; 1.0015x over previous
; __device__ __forceinline__ void s5_prompt_item(ParamsK p, int l, int b, int g, LAS unsigned char* lds) {
;     ...
;     const int lg = l * 64 + g;
;     const f32x4 av = ((const f32x4*)(p->ws + WS_S5A))[lg * 64 + lane];
;     const float abr = av[0], abi = av[1];
;     bf16x8 bm[8];
;     { const bf16_t* bmt = (const bf16_t*)(p->ws + WS_S5BM) + (size_t)lg * 2 * 128 * 16;
; #pragma unroll
;       for (int i = 0; i < 8; ++i) bm[i] = *(const bf16x8*)(bmt + (q >> 1) * 2048 + (i * 16 + r) * 16 + (q & 1) * 8); }
;     const bf16_t* ubase = proj + ((size_t)b * SEQ + r) * NIN + OFF_U + g * 16 + (q & 1) * 8;
;     ...
;     bf16x8 ubn = *(const bf16x8*)S5_UADDR(0);
; __device__ __forceinline__ void phase_mixers(ParamsK p, int l, LAS unsigned char* lds) {
;     ...
;         for (int rep = 0; rep < REP_S5; ++rep) for (int item = bid - half; item < 256; item += G - half) s5_prompt_item(p, l, item >> 6, item & 63, lds);
.LBB0_608:
	v_writelane_b32 v252, s43, 29
	s_or_b64 exec, exec, s[0:1]
	v_readlane_b32 s0, v252, 19
	s_lshl_b32 s4, s0, 8
	v_readlane_b32 s1, v252, 20
	v_writelane_b32 v252, s4, 30
	s_lshl_b32 s94, s0, 6
	s_lshl_b32 s90, s0, 10
	v_writelane_b32 v252, s5, 31
	s_lshl_b32 s91, s0, 7
	v_readlane_b32 s0, v252, 21
	v_readlane_b32 s1, v252, 22
	v_readlane_b32 s55, v252, 26
	v_readlane_b32 s4, v252, 6
	s_waitcnt lgkmcnt(0)
	s_barrier
	s_mov_b32 s95, s53
	s_cmp_ge_i32 s55, s4
	s_mov_b64 s[4:5], -1
	s_cbranch_scc0 .LBB0_634
	v_readlane_b32 s4, v252, 6
	s_sub_i32 s14, s55, s4
	s_cmpk_gt_i32 s14, 0xff
	s_cbranch_scc1 .LBB0_628
	v_readlane_b32 s4, v252, 5
	s_add_i32 s15, s4, s55
	v_readlane_b32 s4, v252, 2
	s_nop 0
	s_cmpk_lg_i32 s4, 0x80
	s_cbranch_scc1 .Ls5_noperm
	s_cmpk_gt_u32 s14, 0x7f
	s_cbranch_scc1 .Ls5_noperm
	s_and_b32 s4, s14, 7
	s_lshl_b32 s4, s4, 4
	s_lshr_b32 s5, s14, 3
	s_or_b32 s4, s4, s5
	s_sub_i32 s5, s4, s14
	s_add_i32 s15, s15, s5
	s_mov_b32 s14, s4
.Ls5_noperm:
.LBB0_611:
	v_mov_b32_e32 v59, v176
	s_load_dwordx2 s[6:7], s[0:1], 0xf8
	s_and_b32 s16, s14, 63
	v_and_b32_e32 v60, 63, v59
	s_or_b32 s52, s16, s94
	s_ashr_i32 s4, s14, 6
	v_lshl_or_b32 v0, s52, 6, v60
	s_lshl_b64 s[8:9], s[52:53], 13
	s_waitcnt lgkmcnt(0)
	v_lshl_add_u64 v[2:3], v[0:1], 4, s[6:7]
	s_add_u32 s8, s6, s8
	v_lshlrev_b32_e32 v0, 7, v59
	s_addc_u32 s9, s7, s9
	v_and_b32_e32 v0, 0x1000, v0
	v_and_b32_e32 v58, 15, v59
	s_mov_b32 s5, 0x35820000
	v_lshl_add_u64 v[6:7], s[8:9], 0, v[0:1]
	v_and_b32_e32 v0, 16, v59
	v_add_co_u32_e32 v2, vcc, s5, v2
	v_lshl_add_u64 v[6:7], v[6:7], 0, v[0:1]
	v_lshlrev_b32_e32 v8, 5, v58
	v_mov_b32_e32 v9, v1
	v_addc_co_u32_e32 v3, vcc, 0, v3, vcc
	v_lshl_add_u64 v[6:7], v[6:7], 0, v[8:9]
	s_mov_b32 s5, 0x359c0000
	s_mov_b64 s[8:9], 0x359c0400
	v_add_co_u32_e32 v30, vcc, s5, v6
	s_ashr_i32 s5, s4, 31
	v_lshl_add_u64 v[34:35], v[6:7], 0, s[8:9]
	s_lshl_b64 s[8:9], s[4:5], 11
	v_addc_co_u32_e32 v31, vcc, 0, v7, vcc
	v_or_b32_e32 v40, s8, v58
	v_mov_b64_e32 v[38:39], s[6:7]
	global_load_dwordx4 v[2:5], v[2:3], off offset:1024
	s_nop 0
	global_load_dwordx4 v[6:9], v[34:35], off offset:512
	global_load_dwordx4 v[10:13], v[34:35], off offset:1024
	global_load_dwordx4 v[14:17], v[34:35], off offset:1536
	global_load_dwordx4 v[18:21], v[34:35], off offset:2048
	global_load_dwordx4 v[22:25], v[34:35], off offset:2560
	global_load_dwordx4 v[26:29], v[34:35], off offset:3072
	s_nop 0
	global_load_dwordx4 v[30:33], v[30:31], off offset:1024
	s_nop 0
	global_load_dwordx4 v[34:37], v[34:35], off offset:3584
	v_mad_u64_u32 v[38:39], s[10:11], v40, s73, v[38:39]
	v_mad_i32_i24 v39, s9, v187, v39
	s_lshl_b32 s10, s16, 5
	s_mov_b32 s11, s53
	v_lshl_add_u64 v[38:39], v[38:39], 0, s[10:11]
	v_lshl_add_u64 v[38:39], v[38:39], 0, v[0:1]
	s_mov_b64 s[10:11], 0x14300000
	v_lshl_add_u64 v[62:63], v[38:39], 0, s[10:11]
	v_and_b32_e32 v64, 0xffffffc0, v59
	v_mad_i64_i32 v[54:55], s[10:11], v64, s73, v[62:63]
	global_load_dwordx4 v[38:41], v[54:55], off
	v_ashrrev_i32_e32 v82, 6, v59
	s_movk_i32 s12, 0x3200
	v_mul_lo_u32 v42, v82, s12
	v_add_u32_e32 v65, 0, v42
	s_movk_i32 s12, 0x210
	v_bfe_u32 v61, v59, 4, 2
	v_and_b32_e32 v0, 48, v59
	v_mad_u32_u24 v43, v58, s12, v65
	v_mov_b32_e32 v42, 0
	s_mov_b32 s10, 16
	s_mov_b32 s11, 2
	v_lshlrev_b32_e32 v46, 3, v61
	v_lshl_add_u32 v83, v60, 2, v65
	s_lshl_b32 s17, s16, 4
	v_add_u32_e32 v84, v43, v0
	v_mov_b32_e32 v43, v42
	s_waitcnt vmcnt(9)
	v_mov_b32_e32 v66, v2
	v_mov_b32_e32 v67, v2
	v_mov_b32_e32 v68, v3
	v_mov_b32_e32 v69, v3
	v_pk_mov_b32 v[70:71], v[2:3], v[2:3] op_sel:[1,0]

; __device__ __forceinline__ void phase_mixers(ParamsK p, int l, LAS unsigned char* lds) {
;     ...
;     if (bid < half) {
;         for (int item = bid; item < 128; item += half) {
;             if (item < 64) recur_item<false>(p, l, item >> 4, (item >> 2) & 3, item & 3, lds);
;             else { const int it = item - 64; recur_item<true>(p, l, it >> 4, (it >> 1) & 7, it & 1, lds); }
.LBB0_634:
	s_and_b64 vcc, exec, s[4:5]
	s_cbranch_vccz .LBB0_654
	s_cmpk_gt_i32 s55, 0x7f
	s_cbranch_scc1 .LBB0_654
	v_readlane_b32 s4, v252, 6
	s_nop 0
	s_cmpk_lg_i32 s4, 0x80
	s_cbranch_scc1 .Lmix_noperm
	s_and_b32 s4, s55, 7
	s_lshl_b32 s4, s4, 3
	s_bfe_u32 s5, s55, 0x30003
	s_or_b32 s4, s4, s5
	s_and_b32 s5, s55, 64
	s_or_b32 s55, s4, s5
.Lmix_noperm:
	v_readlane_b32 s4, v252, 19
	s_lshl_b32 s34, s4, 5
	s_lshl_b32 s35, s4, 2
	s_sub_i32 s36, s55, 64
	s_lshl_b32 s37, s55, 6
	s_mov_b64 s[64:65], 0x23ea0000
	v_readlane_b32 s5, v252, 20
	s_branch .LBB0_638
